# units after an epilogue skip the accumulator zeroing: the first MFMA of each accumulator in the peeled iteration takes C = 0
# speedup vs baseline: 1.0121x; 1.0002x over previous
; #define PG8_STAGE(bufoff, gbase, voff) do { _Pragma("unroll") for (int _i = 0; _i < 2; ++_i) \
;         __builtin_amdgcn_global_load_lds((const unsigned*)((const char*)(gbase) + (voff)[_i]), (LAS unsigned*)(lds + (bufoff) + ldsw + _i * 8192), 16, 0, 0); } while (0)
; #define PG8_LDA(dst, b, h) do { _Pragma("unroll") for (int m = 0; m < 4; ++m) _Pragma("unroll") for (int k = 0; k < 2; ++k) dst[m][k] = *(const LAS bf16x8*)(lds + PG8_SA(b, h) + aoff + m * 2048 + k * 1024); } while (0)
; #define PG8_LDB(dst, b, h) do { _Pragma("unroll") for (int n = 0; n < 2; ++n) _Pragma("unroll") for (int k = 0; k < 2; ++k) dst[n][k] = *(const LAS bf16x8*)(lds + PG8_SB(b, h) + boff + n * 2048 + k * 1024); } while (0)
; #define PG8_MMA(ai, bj, At, Bt) do { __builtin_amdgcn_s_setprio(1); _Pragma("unroll") for (int m = 0; m < 4; ++m) _Pragma("unroll") for (int n = 0; n < 2; ++n) _Pragma("unroll") for (int k = 0; k < 2; ++k) \
;         acc[ai][bj][m][n] = __builtin_amdgcn_mfma_f32_16x16x32_bf16(Bt[n][k], At[m][k], acc[ai][bj][m][n], 0, 0, 0); __builtin_amdgcn_s_setprio(0); } while (0)
; #define PG8_WAIT_V(n) asm volatile("s_waitcnt vmcnt(" #n ")" ::: "memory")
; #define PG8_WAIT_L(n) asm volatile("s_waitcnt lgkmcnt(" #n ")" ::: "memory")
; #define PG8_BAR __builtin_amdgcn_s_barrier()
; #define PG8_SCHED __builtin_amdgcn_sched_barrier(0)
; template <class Epi>
; __device__ __forceinline__ void gemm_phase(LAS unsigned char* lds, const Gemm g, const Epi& E) {
;     ...
;             PG8_LDB(B0, 0, 0); PG8_LDB(B1, 0, 1); PG8_SCHED; PG8_LDA(At, 0, 0); PG8_STAGE(PG8_SA(1, 1), a1 + hstep, voffA);
;             PG8_WAIT_V(8); PG8_WAIT_L(0); PG8_BAR; PG8_MMA(0, 0, At, B0); PG8_MMA(0, 1, At, B1); PG8_BAR; PG8_SCHED;
;             PG8_LDA(At, 0, 1); PG8_STAGE(PG8_SB(0, 0), b2, voffA); PG8_STAGE(PG8_SB(0, 1), b2 + hstep, voffA); PG8_STAGE(PG8_SA(0, 0), a2, voffA);
.Lrw1a_d:
	s_waitcnt lgkmcnt(0)
	s_barrier
	s_waitcnt lgkmcnt(0)
	v_mfma_f32_16x16x32_bf16 v[122:125], v[130:133], v[202:205], 0
	v_mfma_f32_16x16x32_bf16 v[126:129], v[152:155], v[202:205], 0
	v_mfma_f32_16x16x32_bf16 v[106:109], v[130:133], v[210:213], 0
	v_mfma_f32_16x16x32_bf16 v[110:113], v[152:155], v[210:213], 0
	v_mfma_f32_16x16x32_bf16 v[90:93], v[130:133], v[218:221], 0
	v_mfma_f32_16x16x32_bf16 v[94:97], v[152:155], v[218:221], 0
	v_mfma_f32_16x16x32_bf16 v[74:77], v[130:133], v[226:229], 0
	v_mfma_f32_16x16x32_bf16 v[78:81], v[152:155], v[226:229], 0
	v_mfma_f32_16x16x32_bf16 v[122:125], v[134:137], v[206:209], v[122:125]
	v_mfma_f32_16x16x32_bf16 v[126:129], v[156:159], v[206:209], v[126:129]
	v_mfma_f32_16x16x32_bf16 v[106:109], v[134:137], v[214:217], v[106:109]
	v_mfma_f32_16x16x32_bf16 v[110:113], v[156:159], v[214:217], v[110:113]
	v_mfma_f32_16x16x32_bf16 v[90:93], v[134:137], v[222:225], v[90:93]
	v_mfma_f32_16x16x32_bf16 v[94:97], v[156:159], v[222:225], v[94:97]
	v_mfma_f32_16x16x32_bf16 v[74:77], v[134:137], v[230:233], v[74:77]
	v_mfma_f32_16x16x32_bf16 v[78:81], v[156:159], v[230:233], v[78:81]
	v_mfma_f32_16x16x32_bf16 v[114:117], v[160:163], v[202:205], 0
	v_mfma_f32_16x16x32_bf16 v[118:121], v[194:197], v[202:205], 0
	v_mfma_f32_16x16x32_bf16 v[98:101], v[160:163], v[210:213], 0
	v_mfma_f32_16x16x32_bf16 v[102:105], v[194:197], v[210:213], 0
	v_mfma_f32_16x16x32_bf16 v[82:85], v[160:163], v[218:221], 0
	v_mfma_f32_16x16x32_bf16 v[86:89], v[194:197], v[218:221], 0
	v_mfma_f32_16x16x32_bf16 v[66:69], v[160:163], v[226:229], 0
	v_mfma_f32_16x16x32_bf16 v[70:73], v[194:197], v[226:229], 0
	v_mfma_f32_16x16x32_bf16 v[114:117], v[190:193], v[206:209], v[114:117]
	v_mfma_f32_16x16x32_bf16 v[118:121], v[198:201], v[206:209], v[118:121]
	v_mfma_f32_16x16x32_bf16 v[98:101], v[190:193], v[214:217], v[98:101]
	v_mfma_f32_16x16x32_bf16 v[102:105], v[198:201], v[214:217], v[102:105]
	v_mfma_f32_16x16x32_bf16 v[82:85], v[190:193], v[222:225], v[82:85]
	v_mfma_f32_16x16x32_bf16 v[86:89], v[198:201], v[222:225], v[86:89]
	v_mfma_f32_16x16x32_bf16 v[66:69], v[190:193], v[230:233], v[66:69]
	v_mfma_f32_16x16x32_bf16 v[70:73], v[198:201], v[230:233], v[70:73]
	s_barrier
	s_add_i32 s79, s21, s26
	v_lshl_add_u64 v[164:165], s[4:5], 0, v[0:1]
	s_mov_b32 m0, s79
	ds_read_b128 v[202:205], v167 offset:16384
	ds_read_b128 v[206:209], v167 offset:17408
	ds_read_b128 v[210:213], v167 offset:18432
	ds_read_b128 v[214:217], v167 offset:19456
	ds_read_b128 v[218:221], v167 offset:20480
	ds_read_b128 v[222:225], v167 offset:21504
	ds_read_b128 v[226:229], v167 offset:22528
	ds_read_b128 v[230:233], v167 offset:23552
	global_load_lds_dwordx4 v[164:165], off
	s_add_i32 m0, s79, 0x2000
	s_add_u32 vcc_lo, s4, 0x40000
	v_lshl_add_u64 v[168:169], s[4:5], 0, v[146:147]
	s_addc_u32 vcc_hi, s5, 0
	s_add_i32 s25, s25, s26
	global_load_lds_dwordx4 v[168:169], off
	v_lshl_add_u64 v[234:235], vcc, 0, v[0:1]
	s_mov_b32 m0, s25
	v_lshl_add_u64 v[236:237], s[10:11], 0, v[146:147]
	global_load_lds_dwordx4 v[234:235], off
	v_lshl_add_u64 v[234:235], vcc, 0, v[146:147]
	s_add_i32 m0, s25, 0x2000
	s_nop 0
	global_load_lds_dwordx4 v[234:235], off
	v_lshl_add_u64 v[234:235], s[10:11], 0, v[0:1]
	s_mov_b32 m0, s53
	s_nop 0
	global_load_lds_dwordx4 v[234:235], off
	s_mov_b32 m0, s73
	s_nop 0
	global_load_lds_dwordx4 v[236:237], off
	s_cmp_eq_u32 s32, 1
	s_cbranch_scc1 .Lrw1b_1
	s_cmp_eq_u32 s32, 2
	s_cbranch_scc1 .Lrw1b_2
	s_waitcnt vmcnt(63)
	s_branch .Lrw1b_d

; #define PG8_STAGE(bufoff, gbase, voff) do { _Pragma("unroll") for (int _i = 0; _i < 2; ++_i) \
;         __builtin_amdgcn_global_load_lds((const unsigned*)((const char*)(gbase) + (voff)[_i]), (LAS unsigned*)(lds + (bufoff) + ldsw + _i * 8192), 16, 0, 0); } while (0)
; #define PG8_LDA(dst, b, h) do { _Pragma("unroll") for (int m = 0; m < 4; ++m) _Pragma("unroll") for (int k = 0; k < 2; ++k) dst[m][k] = *(const LAS bf16x8*)(lds + PG8_SA(b, h) + aoff + m * 2048 + k * 1024); } while (0)
; #define PG8_LDB(dst, b, h) do { _Pragma("unroll") for (int n = 0; n < 2; ++n) _Pragma("unroll") for (int k = 0; k < 2; ++k) dst[n][k] = *(const LAS bf16x8*)(lds + PG8_SB(b, h) + boff + n * 2048 + k * 1024); } while (0)
; #define PG8_MMA(ai, bj, At, Bt) do { __builtin_amdgcn_s_setprio(1); _Pragma("unroll") for (int m = 0; m < 4; ++m) _Pragma("unroll") for (int n = 0; n < 2; ++n) _Pragma("unroll") for (int k = 0; k < 2; ++k) \
;         acc[ai][bj][m][n] = __builtin_amdgcn_mfma_f32_16x16x32_bf16(Bt[n][k], At[m][k], acc[ai][bj][m][n], 0, 0, 0); __builtin_amdgcn_s_setprio(0); } while (0)
; #define PG8_WAIT_V(n) asm volatile("s_waitcnt vmcnt(" #n ")" ::: "memory")
; #define PG8_WAIT_L(n) asm volatile("s_waitcnt lgkmcnt(" #n ")" ::: "memory")
; #define PG8_BAR __builtin_amdgcn_s_barrier()
; #define PG8_SCHED __builtin_amdgcn_sched_barrier(0)
; template <class Epi>
; __device__ __forceinline__ void gemm_phase(LAS unsigned char* lds, const Gemm g, const Epi& E) {
;     ...
;             PG8_WAIT_V(8); PG8_WAIT_L(0); PG8_BAR; PG8_MMA(1, 0, At, B0); PG8_MMA(1, 1, At, B1); PG8_BAR; PG8_SCHED;
;             PG8_LDB(B0, 1, 0); PG8_LDB(B1, 1, 1); PG8_SCHED; PG8_LDA(At, 1, 0); PG8_STAGE(PG8_SA(0, 1), a2 + hstep, voffA);
;             PG8_WAIT_V(8); PG8_WAIT_L(0); PG8_BAR; PG8_MMA(0, 0, At, B0); PG8_MMA(0, 1, At, B1); PG8_BAR; PG8_SCHED;
.Lrw1b_d:
	s_mov_b32 s32, 0
	s_waitcnt lgkmcnt(0)
	s_barrier
	s_waitcnt lgkmcnt(0)
	v_mfma_f32_16x16x32_bf16 v[58:61], v[130:133], v[202:205], 0
	v_mfma_f32_16x16x32_bf16 v[62:65], v[152:155], v[202:205], 0
	v_mfma_f32_16x16x32_bf16 v[42:45], v[130:133], v[210:213], 0
	v_mfma_f32_16x16x32_bf16 v[46:49], v[152:155], v[210:213], 0
	v_mfma_f32_16x16x32_bf16 v[26:29], v[130:133], v[218:221], 0
	v_mfma_f32_16x16x32_bf16 v[30:33], v[152:155], v[218:221], 0
	v_mfma_f32_16x16x32_bf16 v[10:13], v[130:133], v[226:229], 0
	v_mfma_f32_16x16x32_bf16 v[14:17], v[152:155], v[226:229], 0
	v_mfma_f32_16x16x32_bf16 v[58:61], v[134:137], v[206:209], v[58:61]
	v_mfma_f32_16x16x32_bf16 v[62:65], v[156:159], v[206:209], v[62:65]
	v_mfma_f32_16x16x32_bf16 v[42:45], v[134:137], v[214:217], v[42:45]
	v_mfma_f32_16x16x32_bf16 v[46:49], v[156:159], v[214:217], v[46:49]
	v_mfma_f32_16x16x32_bf16 v[26:29], v[134:137], v[222:225], v[26:29]
	v_mfma_f32_16x16x32_bf16 v[30:33], v[156:159], v[222:225], v[30:33]
	v_mfma_f32_16x16x32_bf16 v[10:13], v[134:137], v[230:233], v[10:13]
	v_mfma_f32_16x16x32_bf16 v[14:17], v[156:159], v[230:233], v[14:17]
	v_mfma_f32_16x16x32_bf16 v[50:53], v[160:163], v[202:205], 0
	v_mfma_f32_16x16x32_bf16 v[54:57], v[194:197], v[202:205], 0
	v_mfma_f32_16x16x32_bf16 v[34:37], v[160:163], v[210:213], 0
	v_mfma_f32_16x16x32_bf16 v[38:41], v[194:197], v[210:213], 0
	v_mfma_f32_16x16x32_bf16 v[18:21], v[160:163], v[218:221], 0
	v_mfma_f32_16x16x32_bf16 v[22:25], v[194:197], v[218:221], 0
	v_mfma_f32_16x16x32_bf16 v[6:9], v[160:163], v[226:229], 0
	v_mfma_f32_16x16x32_bf16 v[2:5], v[194:197], v[226:229], 0
	v_mfma_f32_16x16x32_bf16 v[50:53], v[190:193], v[206:209], v[50:53]
	v_mfma_f32_16x16x32_bf16 v[54:57], v[198:201], v[206:209], v[54:57]
	v_mfma_f32_16x16x32_bf16 v[34:37], v[190:193], v[214:217], v[34:37]
	v_mfma_f32_16x16x32_bf16 v[38:41], v[198:201], v[214:217], v[38:41]
	v_mfma_f32_16x16x32_bf16 v[18:21], v[190:193], v[222:225], v[18:21]
	v_mfma_f32_16x16x32_bf16 v[22:25], v[198:201], v[222:225], v[22:25]
	v_mfma_f32_16x16x32_bf16 v[6:9], v[190:193], v[230:233], v[6:9]
	v_mfma_f32_16x16x32_bf16 v[2:5], v[198:201], v[230:233], v[2:5]
	s_barrier
	s_add_i32 s25, 0, 0x18000
	s_add_i32 s79, 0, 0x1c000
	v_add_u32_e32 v156, s25, v166
	v_add_u32_e32 v189, s79, v166
	ds_read_b128 v[130:133], v156
	ds_read_b128 v[134:137], v156 offset:1024
	ds_read_b128 v[152:155], v156 offset:2048
	ds_read_b128 v[156:159], v156 offset:3072
	ds_read_b128 v[160:163], v189
	ds_read_b128 v[190:193], v189 offset:1024
	ds_read_b128 v[194:197], v189 offset:2048
	ds_read_b128 v[198:201], v189 offset:3072
	s_add_u32 s10, s10, 0x40000
	s_addc_u32 s11, s11, 0
	s_mov_b32 m0, s76
	v_lshl_add_u64 v[238:239], s[10:11], 0, v[0:1]
	ds_read_b128 v[202:205], v167 offset:32768
	ds_read_b128 v[206:209], v167 offset:33792
	ds_read_b128 v[210:213], v167 offset:34816
	ds_read_b128 v[214:217], v167 offset:35840
	ds_read_b128 v[218:221], v167 offset:36864
	ds_read_b128 v[222:225], v167 offset:37888
	ds_read_b128 v[226:229], v167 offset:38912
	ds_read_b128 v[230:233], v167 offset:39936
	global_load_lds_dwordx4 v[238:239], off
	v_lshl_add_u64 v[238:239], s[10:11], 0, v[146:147]
	s_mov_b32 m0, s77
	s_nop 0
	global_load_lds_dwordx4 v[238:239], off
	s_waitcnt vmcnt(8)
	s_waitcnt lgkmcnt(0)
	s_barrier
	s_waitcnt lgkmcnt(0)
	v_mfma_f32_16x16x32_bf16 v[122:125], v[130:133], v[202:205], v[122:125]
	v_mfma_f32_16x16x32_bf16 v[126:129], v[152:155], v[202:205], v[126:129]
	v_mfma_f32_16x16x32_bf16 v[106:109], v[130:133], v[210:213], v[106:109]
	v_mfma_f32_16x16x32_bf16 v[110:113], v[152:155], v[210:213], v[110:113]
	v_mfma_f32_16x16x32_bf16 v[90:93], v[130:133], v[218:221], v[90:93]
	v_mfma_f32_16x16x32_bf16 v[94:97], v[152:155], v[218:221], v[94:97]
	v_mfma_f32_16x16x32_bf16 v[74:77], v[130:133], v[226:229], v[74:77]
	v_mfma_f32_16x16x32_bf16 v[78:81], v[152:155], v[226:229], v[78:81]
	v_mfma_f32_16x16x32_bf16 v[122:125], v[134:137], v[206:209], v[122:125]
	v_mfma_f32_16x16x32_bf16 v[126:129], v[156:159], v[206:209], v[126:129]
	v_mfma_f32_16x16x32_bf16 v[106:109], v[134:137], v[214:217], v[106:109]
	v_mfma_f32_16x16x32_bf16 v[110:113], v[156:159], v[214:217], v[110:113]
	v_mfma_f32_16x16x32_bf16 v[90:93], v[134:137], v[222:225], v[90:93]
	v_mfma_f32_16x16x32_bf16 v[94:97], v[156:159], v[222:225], v[94:97]
	v_mfma_f32_16x16x32_bf16 v[74:77], v[134:137], v[230:233], v[74:77]
	v_mfma_f32_16x16x32_bf16 v[78:81], v[156:159], v[230:233], v[78:81]
	v_mfma_f32_16x16x32_bf16 v[114:117], v[160:163], v[202:205], v[114:117]
	v_mfma_f32_16x16x32_bf16 v[118:121], v[194:197], v[202:205], v[118:121]
	v_mfma_f32_16x16x32_bf16 v[98:101], v[160:163], v[210:213], v[98:101]
	v_mfma_f32_16x16x32_bf16 v[102:105], v[194:197], v[210:213], v[102:105]
	v_mfma_f32_16x16x32_bf16 v[82:85], v[160:163], v[218:221], v[82:85]
	v_mfma_f32_16x16x32_bf16 v[86:89], v[194:197], v[218:221], v[86:89]
	v_mfma_f32_16x16x32_bf16 v[66:69], v[160:163], v[226:229], v[66:69]
	v_mfma_f32_16x16x32_bf16 v[70:73], v[194:197], v[226:229], v[70:73]
	v_mfma_f32_16x16x32_bf16 v[114:117], v[190:193], v[206:209], v[114:117]
	v_mfma_f32_16x16x32_bf16 v[118:121], v[198:201], v[206:209], v[118:121]
	v_mfma_f32_16x16x32_bf16 v[98:101], v[190:193], v[214:217], v[98:101]
	v_mfma_f32_16x16x32_bf16 v[102:105], v[198:201], v[214:217], v[102:105]
	v_mfma_f32_16x16x32_bf16 v[82:85], v[190:193], v[222:225], v[82:85]
	v_mfma_f32_16x16x32_bf16 v[86:89], v[198:201], v[222:225], v[86:89]
	v_mfma_f32_16x16x32_bf16 v[66:69], v[190:193], v[230:233], v[66:69]
	v_mfma_f32_16x16x32_bf16 v[70:73], v[198:201], v[230:233], v[70:73]
	s_barrier
; #define PG8_STAGE(bufoff, gbase, voff) do { _Pragma("unroll") for (int _i = 0; _i < 2; ++_i) \
;         __builtin_amdgcn_global_load_lds((const unsigned*)((const char*)(gbase) + (voff)[_i]), (LAS unsigned*)(lds + (bufoff) + ldsw + _i * 8192), 16, 0, 0); } while (0)
; #define PG8_LDA(dst, b, h) do { _Pragma("unroll") for (int m = 0; m < 4; ++m) _Pragma("unroll") for (int k = 0; k < 2; ++k) dst[m][k] = *(const LAS bf16x8*)(lds + PG8_SA(b, h) + aoff + m * 2048 + k * 1024); } while (0)
; #define PG8_MMA(ai, bj, At, Bt) do { __builtin_amdgcn_s_setprio(1); _Pragma("unroll") for (int m = 0; m < 4; ++m) _Pragma("unroll") for (int n = 0; n < 2; ++n) _Pragma("unroll") for (int k = 0; k < 2; ++k) \
;         acc[ai][bj][m][n] = __builtin_amdgcn_mfma_f32_16x16x32_bf16(Bt[n][k], At[m][k], acc[ai][bj][m][n], 0, 0, 0); __builtin_amdgcn_s_setprio(0); } while (0)
; #define PG8_WAIT_V(n) asm volatile("s_waitcnt vmcnt(" #n ")" ::: "memory")
; #define PG8_WAIT_L(n) asm volatile("s_waitcnt lgkmcnt(" #n ")" ::: "memory")
; #define PG8_BAR __builtin_amdgcn_s_barrier()
; #define PG8_SCHED __builtin_amdgcn_sched_barrier(0)
; template <class Epi>
; __device__ __forceinline__ void gemm_phase(LAS unsigned char* lds, const Gemm g, const Epi& E) {
;     ...
;             PG8_LDA(At, 1, 1); PG8_STAGE(PG8_SB(1, 0), b3, voffA); PG8_STAGE(PG8_SB(1, 1), b3 + hstep, voffA); PG8_STAGE(PG8_SA(1, 0), a3, voffA);
;             PG8_WAIT_V(8); PG8_WAIT_L(0); PG8_BAR; PG8_MMA(1, 0, At, B0); PG8_MMA(1, 1, At, B1); PG8_BAR; PG8_SCHED;
;         }
	s_add_i32 s10, s25, s26
	v_lshl_add_u64 v[164:165], v[164:165], 0, s[80:81]
	s_mov_b32 m0, s10
	ds_read_b128 v[202:205], v167 offset:49152
	ds_read_b128 v[206:209], v167 offset:50176
	ds_read_b128 v[210:213], v167 offset:51200
	ds_read_b128 v[214:217], v167 offset:52224
	ds_read_b128 v[218:221], v167 offset:53248
	ds_read_b128 v[222:225], v167 offset:54272
	ds_read_b128 v[226:229], v167 offset:55296
	ds_read_b128 v[230:233], v167 offset:56320
	global_load_lds_dwordx4 v[164:165], off
	s_add_i32 m0, s10, 0x2000
	s_add_u32 s4, s4, 0x40080
	v_lshl_add_u64 v[164:165], v[168:169], 0, s[80:81]
	s_addc_u32 s5, s5, 0
	s_add_i32 s10, s79, s26
	global_load_lds_dwordx4 v[164:165], off
	v_lshl_add_u64 v[164:165], s[4:5], 0, v[0:1]
	s_mov_b32 m0, s10
	s_nop 0
	global_load_lds_dwordx4 v[164:165], off
	v_lshl_add_u64 v[164:165], s[4:5], 0, v[146:147]
	s_add_i32 m0, s10, 0x2000
	s_nop 0
	global_load_lds_dwordx4 v[164:165], off
	v_lshl_add_u64 v[164:165], v[234:235], 0, s[80:81]
	s_mov_b32 m0, s37
	s_nop 0
	global_load_lds_dwordx4 v[164:165], off
	v_lshl_add_u64 v[164:165], v[236:237], 0, s[80:81]
	s_mov_b32 m0, s93
	s_nop 0
	global_load_lds_dwordx4 v[164:165], off
	s_waitcnt vmcnt(8)
	s_waitcnt lgkmcnt(0)
	s_barrier
	s_waitcnt lgkmcnt(0)
	v_mfma_f32_16x16x32_bf16 v[58:61], v[130:133], v[202:205], v[58:61]
	v_mfma_f32_16x16x32_bf16 v[62:65], v[152:155], v[202:205], v[62:65]
	v_mfma_f32_16x16x32_bf16 v[42:45], v[130:133], v[210:213], v[42:45]
	v_mfma_f32_16x16x32_bf16 v[46:49], v[152:155], v[210:213], v[46:49]
	v_mfma_f32_16x16x32_bf16 v[26:29], v[130:133], v[218:221], v[26:29]
	v_mfma_f32_16x16x32_bf16 v[30:33], v[152:155], v[218:221], v[30:33]
	v_mfma_f32_16x16x32_bf16 v[10:13], v[130:133], v[226:229], v[10:13]
	v_mfma_f32_16x16x32_bf16 v[14:17], v[152:155], v[226:229], v[14:17]
	v_mfma_f32_16x16x32_bf16 v[58:61], v[134:137], v[206:209], v[58:61]
	v_mfma_f32_16x16x32_bf16 v[62:65], v[156:159], v[206:209], v[62:65]
	v_mfma_f32_16x16x32_bf16 v[42:45], v[134:137], v[214:217], v[42:45]
	v_mfma_f32_16x16x32_bf16 v[46:49], v[156:159], v[214:217], v[46:49]
	v_mfma_f32_16x16x32_bf16 v[26:29], v[134:137], v[222:225], v[26:29]
	v_mfma_f32_16x16x32_bf16 v[30:33], v[156:159], v[222:225], v[30:33]
	v_mfma_f32_16x16x32_bf16 v[10:13], v[134:137], v[230:233], v[10:13]
	v_mfma_f32_16x16x32_bf16 v[14:17], v[156:159], v[230:233], v[14:17]
	v_mfma_f32_16x16x32_bf16 v[50:53], v[160:163], v[202:205], v[50:53]
	v_mfma_f32_16x16x32_bf16 v[54:57], v[194:197], v[202:205], v[54:57]
	v_mfma_f32_16x16x32_bf16 v[34:37], v[160:163], v[210:213], v[34:37]
	v_mfma_f32_16x16x32_bf16 v[38:41], v[194:197], v[210:213], v[38:41]
	v_mfma_f32_16x16x32_bf16 v[18:21], v[160:163], v[218:221], v[18:21]
	v_mfma_f32_16x16x32_bf16 v[22:25], v[194:197], v[218:221], v[22:25]
	v_mfma_f32_16x16x32_bf16 v[6:9], v[160:163], v[226:229], v[6:9]
	v_mfma_f32_16x16x32_bf16 v[2:5], v[194:197], v[226:229], v[2:5]
	v_mfma_f32_16x16x32_bf16 v[50:53], v[190:193], v[206:209], v[50:53]
	v_mfma_f32_16x16x32_bf16 v[54:57], v[198:201], v[206:209], v[54:57]
	v_mfma_f32_16x16x32_bf16 v[34:37], v[190:193], v[214:217], v[34:37]
	v_mfma_f32_16x16x32_bf16 v[38:41], v[198:201], v[214:217], v[38:41]
	v_mfma_f32_16x16x32_bf16 v[18:21], v[190:193], v[222:225], v[18:21]
	v_mfma_f32_16x16x32_bf16 v[22:25], v[198:201], v[222:225], v[22:25]
	v_mfma_f32_16x16x32_bf16 v[6:9], v[190:193], v[230:233], v[6:9]
	v_mfma_f32_16x16x32_bf16 v[2:5], v[198:201], v[230:233], v[2:5]
	s_barrier
	s_add_u32 s8, s8, 0x100
	s_addc_u32 s9, s9, 0
	s_add_u32 s71, s71, 0x100
	s_addc_u32 s75, s75, 0
	s_cmp_ge_i32 s78, s72
	s_mov_b32 s4, s78
	s_cbranch_scc0 .LBB0_95
	s_branch .Lk1_exit

; template <class Epi>
; __device__ __forceinline__ void gemm_phase(LAS unsigned char* lds, const Gemm g, const Epi& E) {
;     ...
;         Unit nxt; const bool has_next = get_unit(lds, ui + 1, nxt);
;         const char* nA = has_next ? (const char*)((nxt.sub & 1) ? g.A1 : g.A0) + (size_t)nxt.pm * tstep + (size_t)nxt.kt0 * kstep : cA; const char* nB = has_next ? (const char*)((nxt.sub & 1) ? g.B1 : g.B0) + (size_t)nxt.pn * tstep + (size_t)nxt.kt0 * kstep : cB;
;         const int nt = cur.nt;
;         for (int t = 0; t < nt; t += 2) {
;             const bool last = (t == nt - 2);
;             const char* a1 = cA + (size_t)(t + 1) * kstep;
;             const char* a2 = last ? nA : cA + (size_t)(t + 2) * kstep; const char* b2 = last ? nB : cB + (size_t)(t + 2) * kstep;
;     ...
;         if (!(Epi::KEEP && cur.sub == 0))
; #pragma unroll
;         for (int a = 0; a < 2; ++a)
; #pragma unroll
;             for (int b = 0; b < 2; ++b)
; #pragma unroll
;                 for (int m = 0; m < 4; ++m)
; #pragma unroll
;                     for (int n = 0; n < 2; ++n) acc[a][b][m][n] = (f32x4){0.f, 0.f, 0.f, 0.f};
.LBB0_93:
	s_ashr_i32 s69, s68, 31
	s_lshl_b64 s[10:11], s[68:69], 19
	s_add_u32 s2, s35, s10
	s_addc_u32 s12, s28, s11
	s_ashr_i32 s75, s74, 31
	s_lshl_b64 s[10:11], s[74:75], 7
	s_add_u32 s58, s2, s10
	s_addc_u32 s59, s12, s11
	s_ashr_i32 s71, s70, 31
	s_lshl_b64 s[12:13], s[70:71], 19
	s_add_u32 s2, s29, s12
	s_addc_u32 s12, s45, s13
	s_add_u32 s62, s2, s10
	s_addc_u32 s63, s12, s11
	s_cmp_lt_i32 s72, 1
	s_cbranch_scc1 .LBB0_268
	s_and_b64 s[10:11], s[6:7], exec
	s_cselect_b32 s2, s59, s9
	s_cselect_b32 s12, s58, s8
	s_cselect_b32 s13, s63, s5
	s_cselect_b32 s15, s62, s4
	s_add_i32 s69, s72, -2
	s_add_u32 s8, s8, 0x40080
	s_addc_u32 s9, s9, 0
	s_add_u32 s71, s4, 0x100
	s_addc_u32 s75, s5, 0
	s_mov_b32 s4, 0
	s_cmp_lg_u32 s32, 0
	s_cbranch_scc1 .Lk1_peel
	v_mov_b64_e32 v[2:3], 0
	v_mov_b64_e32 v[4:5], 0
	v_mov_b64_e32 v[6:7], 0
	v_mov_b64_e32 v[8:9], 0
	v_mov_b64_e32 v[10:11], 0
	v_mov_b64_e32 v[12:13], 0
	v_mov_b64_e32 v[14:15], 0
	v_mov_b64_e32 v[16:17], 0
	v_mov_b64_e32 v[18:19], 0
	v_mov_b64_e32 v[20:21], 0
	v_mov_b64_e32 v[22:23], 0
	v_mov_b64_e32 v[24:25], 0
	v_mov_b64_e32 v[26:27], 0
	v_mov_b64_e32 v[28:29], 0
	v_mov_b64_e32 v[30:31], 0
	v_mov_b64_e32 v[32:33], 0
	v_mov_b64_e32 v[34:35], 0
	v_mov_b64_e32 v[36:37], 0
	v_mov_b64_e32 v[38:39], 0
	v_mov_b64_e32 v[40:41], 0
	v_mov_b64_e32 v[42:43], 0
	v_mov_b64_e32 v[44:45], 0
	v_mov_b64_e32 v[46:47], 0
	v_mov_b64_e32 v[48:49], 0
	v_mov_b64_e32 v[50:51], 0
	v_mov_b64_e32 v[52:53], 0
	v_mov_b64_e32 v[54:55], 0
	v_mov_b64_e32 v[56:57], 0
	v_mov_b64_e32 v[58:59], 0
	v_mov_b64_e32 v[60:61], 0
	v_mov_b64_e32 v[62:63], 0
	v_mov_b64_e32 v[64:65], 0
	v_mov_b64_e32 v[66:67], 0
	v_mov_b64_e32 v[68:69], 0
	v_mov_b64_e32 v[70:71], 0
	v_mov_b64_e32 v[72:73], 0
	v_mov_b64_e32 v[74:75], 0
	v_mov_b64_e32 v[76:77], 0
	v_mov_b64_e32 v[78:79], 0
	v_mov_b64_e32 v[80:81], 0
	v_mov_b64_e32 v[82:83], 0
	v_mov_b64_e32 v[84:85], 0
	v_mov_b64_e32 v[86:87], 0
	v_mov_b64_e32 v[88:89], 0
	v_mov_b64_e32 v[90:91], 0
	v_mov_b64_e32 v[92:93], 0
	v_mov_b64_e32 v[94:95], 0
	v_mov_b64_e32 v[96:97], 0
	v_mov_b64_e32 v[98:99], 0
	v_mov_b64_e32 v[100:101], 0
	v_mov_b64_e32 v[102:103], 0
	v_mov_b64_e32 v[104:105], 0
	v_mov_b64_e32 v[106:107], 0
	v_mov_b64_e32 v[108:109], 0
	v_mov_b64_e32 v[110:111], 0
	v_mov_b64_e32 v[112:113], 0
	v_mov_b64_e32 v[114:115], 0
	v_mov_b64_e32 v[116:117], 0
	v_mov_b64_e32 v[118:119], 0
	v_mov_b64_e32 v[120:121], 0
	v_mov_b64_e32 v[122:123], 0
	v_mov_b64_e32 v[124:125], 0
	v_mov_b64_e32 v[126:127], 0
	v_mov_b64_e32 v[128:129], 0
	s_cmp_lg_u32 s32, 0
	s_cbranch_scc1 .Lk1_peel

; #define PG8_STAGE(bufoff, gbase, voff) do { _Pragma("unroll") for (int _i = 0; _i < 2; ++_i) \
;         __builtin_amdgcn_global_load_lds((const unsigned*)((const char*)(gbase) + (voff)[_i]), (LAS unsigned*)(lds + (bufoff) + ldsw + _i * 8192), 16, 0, 0); } while (0)
; #define PG8_LDA(dst, b, h) do { _Pragma("unroll") for (int m = 0; m < 4; ++m) _Pragma("unroll") for (int k = 0; k < 2; ++k) dst[m][k] = *(const LAS bf16x8*)(lds + PG8_SA(b, h) + aoff + m * 2048 + k * 1024); } while (0)
; #define PG8_LDB(dst, b, h) do { _Pragma("unroll") for (int n = 0; n < 2; ++n) _Pragma("unroll") for (int k = 0; k < 2; ++k) dst[n][k] = *(const LAS bf16x8*)(lds + PG8_SB(b, h) + boff + n * 2048 + k * 1024); } while (0)
; #define PG8_MMA(ai, bj, At, Bt) do { __builtin_amdgcn_s_setprio(1); _Pragma("unroll") for (int m = 0; m < 4; ++m) _Pragma("unroll") for (int n = 0; n < 2; ++n) _Pragma("unroll") for (int k = 0; k < 2; ++k) \
;         acc[ai][bj][m][n] = __builtin_amdgcn_mfma_f32_16x16x32_bf16(Bt[n][k], At[m][k], acc[ai][bj][m][n], 0, 0, 0); __builtin_amdgcn_s_setprio(0); } while (0)
; #define PG8_WAIT_V(n) asm volatile("s_waitcnt vmcnt(" #n ")" ::: "memory")
; #define PG8_WAIT_L(n) asm volatile("s_waitcnt lgkmcnt(" #n ")" ::: "memory")
; #define PG8_BAR __builtin_amdgcn_s_barrier()
; #define PG8_SCHED __builtin_amdgcn_sched_barrier(0)
; template <class Epi>
; __device__ __forceinline__ void gemm_phase(LAS unsigned char* lds, const Gemm g, const Epi& E) {
;     ...
;             PG8_LDB(B0, 0, 0); PG8_LDB(B1, 0, 1); PG8_SCHED; PG8_LDA(At, 0, 0); PG8_STAGE(PG8_SA(1, 1), a1 + hstep, voffA);
;             PG8_WAIT_V(8); PG8_WAIT_L(0); PG8_BAR; PG8_MMA(0, 0, At, B0); PG8_MMA(0, 1, At, B1); PG8_BAR; PG8_SCHED;
;             PG8_LDA(At, 0, 1); PG8_STAGE(PG8_SB(0, 0), b2, voffA); PG8_STAGE(PG8_SB(0, 1), b2 + hstep, voffA); PG8_STAGE(PG8_SA(0, 0), a2, voffA);
.Lrw3a_d:
	s_waitcnt lgkmcnt(0)
	s_barrier
	s_waitcnt lgkmcnt(0)
	v_mfma_f32_16x16x32_bf16 v[126:129], v[146:149], v[198:201], 0
	v_mfma_f32_16x16x32_bf16 v[118:121], v[154:157], v[198:201], 0
	v_mfma_f32_16x16x32_bf16 v[110:113], v[146:149], v[206:209], 0
	v_mfma_f32_16x16x32_bf16 v[102:105], v[154:157], v[206:209], 0
	v_mfma_f32_16x16x32_bf16 v[94:97], v[146:149], v[214:217], 0
	v_mfma_f32_16x16x32_bf16 v[86:89], v[154:157], v[214:217], 0
	v_mfma_f32_16x16x32_bf16 v[78:81], v[146:149], v[222:225], 0
	v_mfma_f32_16x16x32_bf16 v[70:73], v[154:157], v[222:225], 0
	v_mfma_f32_16x16x32_bf16 v[126:129], v[150:153], v[202:205], v[126:129]
	v_mfma_f32_16x16x32_bf16 v[118:121], v[158:161], v[202:205], v[118:121]
	v_mfma_f32_16x16x32_bf16 v[110:113], v[150:153], v[210:213], v[110:113]
	v_mfma_f32_16x16x32_bf16 v[102:105], v[158:161], v[210:213], v[102:105]
	v_mfma_f32_16x16x32_bf16 v[94:97], v[150:153], v[218:221], v[94:97]
	v_mfma_f32_16x16x32_bf16 v[86:89], v[158:161], v[218:221], v[86:89]
	v_mfma_f32_16x16x32_bf16 v[78:81], v[150:153], v[226:229], v[78:81]
	v_mfma_f32_16x16x32_bf16 v[70:73], v[158:161], v[226:229], v[70:73]
	v_mfma_f32_16x16x32_bf16 v[122:125], v[162:165], v[198:201], 0
	v_mfma_f32_16x16x32_bf16 v[114:117], v[190:193], v[198:201], 0
	v_mfma_f32_16x16x32_bf16 v[106:109], v[162:165], v[206:209], 0
	v_mfma_f32_16x16x32_bf16 v[98:101], v[190:193], v[206:209], 0
	v_mfma_f32_16x16x32_bf16 v[90:93], v[162:165], v[214:217], 0
	v_mfma_f32_16x16x32_bf16 v[82:85], v[190:193], v[214:217], 0
	v_mfma_f32_16x16x32_bf16 v[74:77], v[162:165], v[222:225], 0
	v_mfma_f32_16x16x32_bf16 v[66:69], v[190:193], v[222:225], 0
	v_mfma_f32_16x16x32_bf16 v[122:125], v[166:169], v[202:205], v[122:125]
	v_mfma_f32_16x16x32_bf16 v[114:117], v[194:197], v[202:205], v[114:117]
	v_mfma_f32_16x16x32_bf16 v[106:109], v[166:169], v[210:213], v[106:109]
	v_mfma_f32_16x16x32_bf16 v[98:101], v[194:197], v[210:213], v[98:101]
	v_mfma_f32_16x16x32_bf16 v[90:93], v[166:169], v[218:221], v[90:93]
	v_mfma_f32_16x16x32_bf16 v[82:85], v[194:197], v[218:221], v[82:85]
	v_mfma_f32_16x16x32_bf16 v[74:77], v[166:169], v[226:229], v[74:77]
	v_mfma_f32_16x16x32_bf16 v[66:69], v[194:197], v[226:229], v[66:69]
	s_barrier
	s_add_i32 s72, s21, s2
	v_lshl_add_u64 v[136:137], s[4:5], 0, v[0:1]
	s_mov_b32 m0, s72
	ds_read_b128 v[198:201], v145 offset:16384
	ds_read_b128 v[202:205], v145 offset:17408
	ds_read_b128 v[206:209], v145 offset:18432
	ds_read_b128 v[210:213], v145 offset:19456
	ds_read_b128 v[214:217], v145 offset:20480
	ds_read_b128 v[218:221], v145 offset:21504
	ds_read_b128 v[222:225], v145 offset:22528
	ds_read_b128 v[226:229], v145 offset:23552
	global_load_lds_dwordx4 v[136:137], off
	s_add_i32 m0, s72, 0x2000
	s_add_u32 s72, s4, 0x40000
	v_lshl_add_u64 v[230:231], s[4:5], 0, v[130:131]
	s_addc_u32 s73, s5, 0
	s_add_i32 s25, s25, s2
	global_load_lds_dwordx4 v[230:231], off
	v_lshl_add_u64 v[232:233], s[72:73], 0, v[0:1]
	s_mov_b32 m0, s25
	v_lshl_add_u64 v[234:235], s[70:71], 0, v[130:131]
	global_load_lds_dwordx4 v[232:233], off
	v_lshl_add_u64 v[232:233], s[72:73], 0, v[130:131]
	s_add_i32 m0, s25, 0x2000
	s_nop 0
	global_load_lds_dwordx4 v[232:233], off
	v_lshl_add_u64 v[232:233], s[70:71], 0, v[0:1]
	s_mov_b32 m0, s7
	s_nop 0
	global_load_lds_dwordx4 v[232:233], off
	s_mov_b32 m0, s9
	s_nop 0
	global_load_lds_dwordx4 v[234:235], off
	s_cmp_eq_u32 s32, 1
	s_cbranch_scc1 .Lrw3b_1
	s_waitcnt vmcnt(16)
	s_branch .Lrw3b_d

; #define PG8_STAGE(bufoff, gbase, voff) do { _Pragma("unroll") for (int _i = 0; _i < 2; ++_i) \
;         __builtin_amdgcn_global_load_lds((const unsigned*)((const char*)(gbase) + (voff)[_i]), (LAS unsigned*)(lds + (bufoff) + ldsw + _i * 8192), 16, 0, 0); } while (0)
; #define PG8_LDA(dst, b, h) do { _Pragma("unroll") for (int m = 0; m < 4; ++m) _Pragma("unroll") for (int k = 0; k < 2; ++k) dst[m][k] = *(const LAS bf16x8*)(lds + PG8_SA(b, h) + aoff + m * 2048 + k * 1024); } while (0)
; #define PG8_LDB(dst, b, h) do { _Pragma("unroll") for (int n = 0; n < 2; ++n) _Pragma("unroll") for (int k = 0; k < 2; ++k) dst[n][k] = *(const LAS bf16x8*)(lds + PG8_SB(b, h) + boff + n * 2048 + k * 1024); } while (0)
; #define PG8_MMA(ai, bj, At, Bt) do { __builtin_amdgcn_s_setprio(1); _Pragma("unroll") for (int m = 0; m < 4; ++m) _Pragma("unroll") for (int n = 0; n < 2; ++n) _Pragma("unroll") for (int k = 0; k < 2; ++k) \
;         acc[ai][bj][m][n] = __builtin_amdgcn_mfma_f32_16x16x32_bf16(Bt[n][k], At[m][k], acc[ai][bj][m][n], 0, 0, 0); __builtin_amdgcn_s_setprio(0); } while (0)
; #define PG8_WAIT_V(n) asm volatile("s_waitcnt vmcnt(" #n ")" ::: "memory")
; #define PG8_WAIT_L(n) asm volatile("s_waitcnt lgkmcnt(" #n ")" ::: "memory")
; #define PG8_BAR __builtin_amdgcn_s_barrier()
; #define PG8_SCHED __builtin_amdgcn_sched_barrier(0)
; template <class Epi>
; __device__ __forceinline__ void gemm_phase(LAS unsigned char* lds, const Gemm g, const Epi& E) {
;     ...
;             PG8_WAIT_V(8); PG8_WAIT_L(0); PG8_BAR; PG8_MMA(1, 0, At, B0); PG8_MMA(1, 1, At, B1); PG8_BAR; PG8_SCHED;
;             PG8_LDB(B0, 1, 0); PG8_LDB(B1, 1, 1); PG8_SCHED; PG8_LDA(At, 1, 0); PG8_STAGE(PG8_SA(0, 1), a2 + hstep, voffA);
;             PG8_WAIT_V(8); PG8_WAIT_L(0); PG8_BAR; PG8_MMA(0, 0, At, B0); PG8_MMA(0, 1, At, B1); PG8_BAR; PG8_SCHED;
.Lrw3b_d:
	s_mov_b32 s32, 0
	s_waitcnt lgkmcnt(0)
	s_barrier
	s_waitcnt lgkmcnt(0)
	v_mfma_f32_16x16x32_bf16 v[62:65], v[146:149], v[198:201], 0
	v_mfma_f32_16x16x32_bf16 v[54:57], v[154:157], v[198:201], 0
	v_mfma_f32_16x16x32_bf16 v[46:49], v[146:149], v[206:209], 0
	v_mfma_f32_16x16x32_bf16 v[38:41], v[154:157], v[206:209], 0
	v_mfma_f32_16x16x32_bf16 v[30:33], v[146:149], v[214:217], 0
	v_mfma_f32_16x16x32_bf16 v[22:25], v[154:157], v[214:217], 0
	v_mfma_f32_16x16x32_bf16 v[14:17], v[146:149], v[222:225], 0
	v_mfma_f32_16x16x32_bf16 v[6:9], v[154:157], v[222:225], 0
	v_mfma_f32_16x16x32_bf16 v[62:65], v[150:153], v[202:205], v[62:65]
	v_mfma_f32_16x16x32_bf16 v[54:57], v[158:161], v[202:205], v[54:57]
	v_mfma_f32_16x16x32_bf16 v[46:49], v[150:153], v[210:213], v[46:49]
	v_mfma_f32_16x16x32_bf16 v[38:41], v[158:161], v[210:213], v[38:41]
	v_mfma_f32_16x16x32_bf16 v[30:33], v[150:153], v[218:221], v[30:33]
	v_mfma_f32_16x16x32_bf16 v[22:25], v[158:161], v[218:221], v[22:25]
	v_mfma_f32_16x16x32_bf16 v[14:17], v[150:153], v[226:229], v[14:17]
	v_mfma_f32_16x16x32_bf16 v[6:9], v[158:161], v[226:229], v[6:9]
	v_mfma_f32_16x16x32_bf16 v[58:61], v[162:165], v[198:201], 0
	v_mfma_f32_16x16x32_bf16 v[50:53], v[190:193], v[198:201], 0
	v_mfma_f32_16x16x32_bf16 v[42:45], v[162:165], v[206:209], 0
	v_mfma_f32_16x16x32_bf16 v[34:37], v[190:193], v[206:209], 0
	v_mfma_f32_16x16x32_bf16 v[26:29], v[162:165], v[214:217], 0
	v_mfma_f32_16x16x32_bf16 v[18:21], v[190:193], v[214:217], 0
	v_mfma_f32_16x16x32_bf16 v[10:13], v[162:165], v[222:225], 0
	v_mfma_f32_16x16x32_bf16 v[2:5], v[190:193], v[222:225], 0
	v_mfma_f32_16x16x32_bf16 v[58:61], v[166:169], v[202:205], v[58:61]
	v_mfma_f32_16x16x32_bf16 v[50:53], v[194:197], v[202:205], v[50:53]
	v_mfma_f32_16x16x32_bf16 v[42:45], v[166:169], v[210:213], v[42:45]
	v_mfma_f32_16x16x32_bf16 v[34:37], v[194:197], v[210:213], v[34:37]
	v_mfma_f32_16x16x32_bf16 v[26:29], v[166:169], v[218:221], v[26:29]
	v_mfma_f32_16x16x32_bf16 v[18:21], v[194:197], v[218:221], v[18:21]
	v_mfma_f32_16x16x32_bf16 v[10:13], v[166:169], v[226:229], v[10:13]
	v_mfma_f32_16x16x32_bf16 v[2:5], v[194:197], v[226:229], v[2:5]
	s_barrier
	s_add_i32 s25, 0, 0x18000
	s_add_i32 s72, 0, 0x1c000
	v_add_u32_e32 v158, s25, v144
	v_add_u32_e32 v189, s72, v144
	ds_read_b128 v[146:149], v158
	ds_read_b128 v[150:153], v158 offset:1024
	ds_read_b128 v[154:157], v158 offset:2048
	ds_read_b128 v[158:161], v158 offset:3072
	ds_read_b128 v[162:165], v189
	ds_read_b128 v[166:169], v189 offset:1024
	ds_read_b128 v[190:193], v189 offset:2048
	ds_read_b128 v[194:197], v189 offset:3072
	s_add_u32 s70, s70, 0x40000
	s_addc_u32 s71, s71, 0
	s_mov_b32 m0, s45
	v_lshl_add_u64 v[236:237], s[70:71], 0, v[0:1]
	ds_read_b128 v[198:201], v145 offset:32768
	ds_read_b128 v[202:205], v145 offset:33792
	ds_read_b128 v[206:209], v145 offset:34816
	ds_read_b128 v[210:213], v145 offset:35840
	ds_read_b128 v[214:217], v145 offset:36864
	ds_read_b128 v[218:221], v145 offset:37888
	ds_read_b128 v[222:225], v145 offset:38912
	ds_read_b128 v[226:229], v145 offset:39936
	global_load_lds_dwordx4 v[236:237], off
	v_lshl_add_u64 v[236:237], s[70:71], 0, v[130:131]
	s_mov_b32 m0, s52
	s_nop 0
	global_load_lds_dwordx4 v[236:237], off
	s_waitcnt vmcnt(8)
	s_waitcnt lgkmcnt(0)
	s_barrier
	s_waitcnt lgkmcnt(0)
	v_mfma_f32_16x16x32_bf16 v[126:129], v[146:149], v[198:201], v[126:129]
	v_mfma_f32_16x16x32_bf16 v[118:121], v[154:157], v[198:201], v[118:121]
	v_mfma_f32_16x16x32_bf16 v[110:113], v[146:149], v[206:209], v[110:113]
	v_mfma_f32_16x16x32_bf16 v[102:105], v[154:157], v[206:209], v[102:105]
	v_mfma_f32_16x16x32_bf16 v[94:97], v[146:149], v[214:217], v[94:97]
	v_mfma_f32_16x16x32_bf16 v[86:89], v[154:157], v[214:217], v[86:89]
	v_mfma_f32_16x16x32_bf16 v[78:81], v[146:149], v[222:225], v[78:81]
	v_mfma_f32_16x16x32_bf16 v[70:73], v[154:157], v[222:225], v[70:73]
	v_mfma_f32_16x16x32_bf16 v[126:129], v[150:153], v[202:205], v[126:129]
	v_mfma_f32_16x16x32_bf16 v[118:121], v[158:161], v[202:205], v[118:121]
	v_mfma_f32_16x16x32_bf16 v[110:113], v[150:153], v[210:213], v[110:113]
	v_mfma_f32_16x16x32_bf16 v[102:105], v[158:161], v[210:213], v[102:105]
	v_mfma_f32_16x16x32_bf16 v[94:97], v[150:153], v[218:221], v[94:97]
	v_mfma_f32_16x16x32_bf16 v[86:89], v[158:161], v[218:221], v[86:89]
	v_mfma_f32_16x16x32_bf16 v[78:81], v[150:153], v[226:229], v[78:81]
	v_mfma_f32_16x16x32_bf16 v[70:73], v[158:161], v[226:229], v[70:73]
	v_mfma_f32_16x16x32_bf16 v[122:125], v[162:165], v[198:201], v[122:125]
	v_mfma_f32_16x16x32_bf16 v[114:117], v[190:193], v[198:201], v[114:117]
	v_mfma_f32_16x16x32_bf16 v[106:109], v[162:165], v[206:209], v[106:109]
	v_mfma_f32_16x16x32_bf16 v[98:101], v[190:193], v[206:209], v[98:101]
	v_mfma_f32_16x16x32_bf16 v[90:93], v[162:165], v[214:217], v[90:93]
	v_mfma_f32_16x16x32_bf16 v[82:85], v[190:193], v[214:217], v[82:85]
	v_mfma_f32_16x16x32_bf16 v[74:77], v[162:165], v[222:225], v[74:77]
	v_mfma_f32_16x16x32_bf16 v[66:69], v[190:193], v[222:225], v[66:69]
	v_mfma_f32_16x16x32_bf16 v[122:125], v[166:169], v[202:205], v[122:125]
	v_mfma_f32_16x16x32_bf16 v[114:117], v[194:197], v[202:205], v[114:117]
	v_mfma_f32_16x16x32_bf16 v[106:109], v[166:169], v[210:213], v[106:109]
	v_mfma_f32_16x16x32_bf16 v[98:101], v[194:197], v[210:213], v[98:101]
	v_mfma_f32_16x16x32_bf16 v[90:93], v[166:169], v[218:221], v[90:93]
	v_mfma_f32_16x16x32_bf16 v[82:85], v[194:197], v[218:221], v[82:85]
	v_mfma_f32_16x16x32_bf16 v[74:77], v[166:169], v[226:229], v[74:77]
	v_mfma_f32_16x16x32_bf16 v[66:69], v[194:197], v[226:229], v[66:69]
	s_barrier
; #define PG8_STAGE(bufoff, gbase, voff) do { _Pragma("unroll") for (int _i = 0; _i < 2; ++_i) \
;         __builtin_amdgcn_global_load_lds((const unsigned*)((const char*)(gbase) + (voff)[_i]), (LAS unsigned*)(lds + (bufoff) + ldsw + _i * 8192), 16, 0, 0); } while (0)
; #define PG8_LDA(dst, b, h) do { _Pragma("unroll") for (int m = 0; m < 4; ++m) _Pragma("unroll") for (int k = 0; k < 2; ++k) dst[m][k] = *(const LAS bf16x8*)(lds + PG8_SA(b, h) + aoff + m * 2048 + k * 1024); } while (0)
; #define PG8_MMA(ai, bj, At, Bt) do { __builtin_amdgcn_s_setprio(1); _Pragma("unroll") for (int m = 0; m < 4; ++m) _Pragma("unroll") for (int n = 0; n < 2; ++n) _Pragma("unroll") for (int k = 0; k < 2; ++k) \
;         acc[ai][bj][m][n] = __builtin_amdgcn_mfma_f32_16x16x32_bf16(Bt[n][k], At[m][k], acc[ai][bj][m][n], 0, 0, 0); __builtin_amdgcn_s_setprio(0); } while (0)
; #define PG8_WAIT_V(n) asm volatile("s_waitcnt vmcnt(" #n ")" ::: "memory")
; #define PG8_WAIT_L(n) asm volatile("s_waitcnt lgkmcnt(" #n ")" ::: "memory")
; #define PG8_BAR __builtin_amdgcn_s_barrier()
; #define PG8_SCHED __builtin_amdgcn_sched_barrier(0)
; template <class Epi>
; __device__ __forceinline__ void gemm_phase(LAS unsigned char* lds, const Gemm g, const Epi& E) {
;     ...
;             PG8_LDA(At, 1, 1); PG8_STAGE(PG8_SB(1, 0), b3, voffA); PG8_STAGE(PG8_SB(1, 1), b3 + hstep, voffA); PG8_STAGE(PG8_SA(1, 0), a3, voffA);
;             PG8_WAIT_V(8); PG8_WAIT_L(0); PG8_BAR; PG8_MMA(1, 0, At, B0); PG8_MMA(1, 1, At, B1); PG8_BAR; PG8_SCHED;
;         }
	s_add_i32 s25, s25, s2
	v_lshl_add_u64 v[136:137], v[136:137], 0, s[80:81]
	s_mov_b32 m0, s25
	ds_read_b128 v[198:201], v145 offset:49152
	ds_read_b128 v[202:205], v145 offset:50176
	ds_read_b128 v[206:209], v145 offset:51200
	ds_read_b128 v[210:213], v145 offset:52224
	ds_read_b128 v[214:217], v145 offset:53248
	ds_read_b128 v[218:221], v145 offset:54272
	ds_read_b128 v[222:225], v145 offset:55296
	ds_read_b128 v[226:229], v145 offset:56320
	global_load_lds_dwordx4 v[136:137], off
	s_add_i32 m0, s25, 0x2000
	s_add_u32 s4, s4, 0x40080
	v_lshl_add_u64 v[136:137], v[230:231], 0, s[80:81]
	s_addc_u32 s5, s5, 0
	s_add_i32 s25, s72, s2
	global_load_lds_dwordx4 v[136:137], off
	v_lshl_add_u64 v[136:137], s[4:5], 0, v[0:1]
	s_mov_b32 m0, s25
	s_nop 0
	global_load_lds_dwordx4 v[136:137], off
	v_lshl_add_u64 v[136:137], s[4:5], 0, v[130:131]
	s_add_i32 m0, s25, 0x2000
	s_nop 0
	global_load_lds_dwordx4 v[136:137], off
	v_lshl_add_u64 v[136:137], v[232:233], 0, s[80:81]
	s_mov_b32 m0, s75
	s_nop 0
	global_load_lds_dwordx4 v[136:137], off
	v_lshl_add_u64 v[136:137], v[234:235], 0, s[80:81]
	s_mov_b32 m0, s76
	s_nop 0
	global_load_lds_dwordx4 v[136:137], off
	s_waitcnt vmcnt(8)
	s_waitcnt lgkmcnt(0)
	s_barrier
	s_waitcnt lgkmcnt(0)
	v_mfma_f32_16x16x32_bf16 v[62:65], v[146:149], v[198:201], v[62:65]
	v_mfma_f32_16x16x32_bf16 v[54:57], v[154:157], v[198:201], v[54:57]
	v_mfma_f32_16x16x32_bf16 v[46:49], v[146:149], v[206:209], v[46:49]
	v_mfma_f32_16x16x32_bf16 v[38:41], v[154:157], v[206:209], v[38:41]
	v_mfma_f32_16x16x32_bf16 v[30:33], v[146:149], v[214:217], v[30:33]
	v_mfma_f32_16x16x32_bf16 v[22:25], v[154:157], v[214:217], v[22:25]
	v_mfma_f32_16x16x32_bf16 v[14:17], v[146:149], v[222:225], v[14:17]
	v_mfma_f32_16x16x32_bf16 v[6:9], v[154:157], v[222:225], v[6:9]
	v_mfma_f32_16x16x32_bf16 v[62:65], v[150:153], v[202:205], v[62:65]
	v_mfma_f32_16x16x32_bf16 v[54:57], v[158:161], v[202:205], v[54:57]
	v_mfma_f32_16x16x32_bf16 v[46:49], v[150:153], v[210:213], v[46:49]
	v_mfma_f32_16x16x32_bf16 v[38:41], v[158:161], v[210:213], v[38:41]
	v_mfma_f32_16x16x32_bf16 v[30:33], v[150:153], v[218:221], v[30:33]
	v_mfma_f32_16x16x32_bf16 v[22:25], v[158:161], v[218:221], v[22:25]
	v_mfma_f32_16x16x32_bf16 v[14:17], v[150:153], v[226:229], v[14:17]
	v_mfma_f32_16x16x32_bf16 v[6:9], v[158:161], v[226:229], v[6:9]
	v_mfma_f32_16x16x32_bf16 v[58:61], v[162:165], v[198:201], v[58:61]
	v_mfma_f32_16x16x32_bf16 v[50:53], v[190:193], v[198:201], v[50:53]
	v_mfma_f32_16x16x32_bf16 v[42:45], v[162:165], v[206:209], v[42:45]
	v_mfma_f32_16x16x32_bf16 v[34:37], v[190:193], v[206:209], v[34:37]
	v_mfma_f32_16x16x32_bf16 v[26:29], v[162:165], v[214:217], v[26:29]
	v_mfma_f32_16x16x32_bf16 v[18:21], v[190:193], v[214:217], v[18:21]
	v_mfma_f32_16x16x32_bf16 v[10:13], v[162:165], v[222:225], v[10:13]
	v_mfma_f32_16x16x32_bf16 v[2:5], v[190:193], v[222:225], v[2:5]
	v_mfma_f32_16x16x32_bf16 v[58:61], v[166:169], v[202:205], v[58:61]
	v_mfma_f32_16x16x32_bf16 v[50:53], v[194:197], v[202:205], v[50:53]
	v_mfma_f32_16x16x32_bf16 v[42:45], v[166:169], v[210:213], v[42:45]
	v_mfma_f32_16x16x32_bf16 v[34:37], v[194:197], v[210:213], v[34:37]
	v_mfma_f32_16x16x32_bf16 v[26:29], v[166:169], v[218:221], v[26:29]
	v_mfma_f32_16x16x32_bf16 v[18:21], v[194:197], v[218:221], v[18:21]
	v_mfma_f32_16x16x32_bf16 v[10:13], v[166:169], v[226:229], v[10:13]
	v_mfma_f32_16x16x32_bf16 v[2:5], v[194:197], v[226:229], v[2:5]
	s_barrier
	s_add_u32 s68, s68, 0x100
	s_addc_u32 s69, s69, 0
	s_add_u32 s93, s93, 0x100
	s_addc_u32 vcc_lo, vcc_lo, 0
	s_cmp_ge_i32 vcc_hi, s37
	s_mov_b32 s4, vcc_hi
	s_cbranch_scc0 .LBB0_441
	s_branch .Lk3_exit

; template <class Epi>
; __device__ __forceinline__ void gemm_phase(LAS unsigned char* lds, const Gemm g, const Epi& E) {
;     ...
;         Unit nxt; const bool has_next = get_unit(lds, ui + 1, nxt);
;         const char* nA = has_next ? (const char*)((nxt.sub & 1) ? g.A1 : g.A0) + (size_t)nxt.pm * tstep + (size_t)nxt.kt0 * kstep : cA; const char* nB = has_next ? (const char*)((nxt.sub & 1) ? g.B1 : g.B0) + (size_t)nxt.pn * tstep + (size_t)nxt.kt0 * kstep : cB;
;         const int nt = cur.nt;
;         for (int t = 0; t < nt; t += 2) {
;             const bool last = (t == nt - 2);
;             const char* a1 = cA + (size_t)(t + 1) * kstep;
;             const char* a2 = last ? nA : cA + (size_t)(t + 2) * kstep; const char* b2 = last ? nB : cB + (size_t)(t + 2) * kstep;
;     ...
;         if (!(Epi::KEEP && cur.sub == 0))
; #pragma unroll
;         for (int a = 0; a < 2; ++a)
; #pragma unroll
;             for (int b = 0; b < 2; ++b)
; #pragma unroll
;                 for (int m = 0; m < 4; ++m)
; #pragma unroll
;                     for (int n = 0; n < 2; ++n) acc[a][b][m][n] = (f32x4){0.f, 0.f, 0.f, 0.f};
.LBB0_439:
	s_ashr_i32 s15, s14, 31
	s_lshl_b64 s[58:59], s[14:15], 19
	s_add_u32 s15, s35, s58
	s_addc_u32 s55, s28, s59
	s_ashr_i32 s57, s56, 31
	s_lshl_b64 s[62:63], s[56:57], 7
	s_add_u32 s58, s15, s62
	s_addc_u32 s59, s55, s63
	s_ashr_i32 s55, s54, 31
	s_lshl_b64 s[70:71], s[54:55], 19
	s_add_u32 s15, s20, s70
	s_addc_u32 s55, s26, s71
	s_add_u32 s62, s15, s62
	s_addc_u32 s63, s55, s63
	s_cmp_lt_i32 s37, 1
	s_cbranch_scc1 .LBB0_449
	s_and_b64 s[70:71], s[66:67], exec
	s_cselect_b32 s15, s59, s69
	s_cselect_b32 s55, s58, s68
	s_cselect_b32 s57, s63, s5
	s_cselect_b32 s82, s62, s4
	s_add_i32 s92, s37, -2
	s_add_u32 s68, s68, 0x40080
	s_addc_u32 s69, s69, 0
	s_add_u32 s93, s4, 0x100
	s_addc_u32 vcc_lo, s5, 0
	s_mov_b32 s4, 0
	s_cmp_lg_u32 s32, 0
	s_cbranch_scc1 .Lk3_peel
	v_mov_b64_e32 v[2:3], 0
	v_mov_b64_e32 v[4:5], 0
	v_mov_b64_e32 v[6:7], 0
	v_mov_b64_e32 v[8:9], 0
	v_mov_b64_e32 v[10:11], 0
	v_mov_b64_e32 v[12:13], 0
	v_mov_b64_e32 v[14:15], 0
	v_mov_b64_e32 v[16:17], 0
	v_mov_b64_e32 v[18:19], 0
	v_mov_b64_e32 v[20:21], 0
	v_mov_b64_e32 v[22:23], 0
	v_mov_b64_e32 v[24:25], 0
	v_mov_b64_e32 v[26:27], 0
	v_mov_b64_e32 v[28:29], 0
	v_mov_b64_e32 v[30:31], 0
	v_mov_b64_e32 v[32:33], 0
	v_mov_b64_e32 v[34:35], 0
	v_mov_b64_e32 v[36:37], 0
	v_mov_b64_e32 v[38:39], 0
	v_mov_b64_e32 v[40:41], 0
	v_mov_b64_e32 v[42:43], 0
	v_mov_b64_e32 v[44:45], 0
	v_mov_b64_e32 v[46:47], 0
	v_mov_b64_e32 v[48:49], 0
	v_mov_b64_e32 v[50:51], 0
	v_mov_b64_e32 v[52:53], 0
	v_mov_b64_e32 v[54:55], 0
	v_mov_b64_e32 v[56:57], 0
	v_mov_b64_e32 v[58:59], 0
	v_mov_b64_e32 v[60:61], 0
	v_mov_b64_e32 v[62:63], 0
	v_mov_b64_e32 v[64:65], 0
	v_mov_b64_e32 v[66:67], 0
	v_mov_b64_e32 v[68:69], 0
	v_mov_b64_e32 v[70:71], 0
	v_mov_b64_e32 v[72:73], 0
	v_mov_b64_e32 v[74:75], 0
	v_mov_b64_e32 v[76:77], 0
	v_mov_b64_e32 v[78:79], 0
	v_mov_b64_e32 v[80:81], 0
	v_mov_b64_e32 v[82:83], 0
	v_mov_b64_e32 v[84:85], 0
	v_mov_b64_e32 v[86:87], 0
	v_mov_b64_e32 v[88:89], 0
	v_mov_b64_e32 v[90:91], 0
	v_mov_b64_e32 v[92:93], 0
	v_mov_b64_e32 v[94:95], 0
	v_mov_b64_e32 v[96:97], 0
	v_mov_b64_e32 v[98:99], 0
	v_mov_b64_e32 v[100:101], 0
	v_mov_b64_e32 v[102:103], 0
	v_mov_b64_e32 v[104:105], 0
	v_mov_b64_e32 v[106:107], 0
	v_mov_b64_e32 v[108:109], 0
	v_mov_b64_e32 v[110:111], 0
	v_mov_b64_e32 v[112:113], 0
	v_mov_b64_e32 v[114:115], 0
	v_mov_b64_e32 v[116:117], 0
	v_mov_b64_e32 v[118:119], 0
	v_mov_b64_e32 v[120:121], 0
	v_mov_b64_e32 v[122:123], 0
	v_mov_b64_e32 v[124:125], 0
	v_mov_b64_e32 v[126:127], 0
	v_mov_b64_e32 v[128:129], 0
	s_cmp_lg_u32 s32, 0
	s_cbranch_scc1 .Lk3_peel
